# EpiUpConv: weight fetch hoisted to the top of each tile (before its K loop), epilogue only spreads it through LDS
# speedup vs baseline: 1.0101x; 1.0101x over previous
;     __device__ __forceinline__ bool next(int i, Unit& u) const {
;         const int L = i * G + c, nmain = nM * 22;
;         if (L < nmain) { int pm, pn; pg8::tile_of(L, nM, 22, pm, pn); u.A = H + (size_t)pm * 256 * 1024; u.B = B + (size_t)pn * 256 * 1024; u.nt = 16; u.pm = pm; u.pn = pn; u.mode = 0; return true; }
;         const int Lb = L - nmain; if (Lb >= 110) return false;
;         const int mt = Lb / 22, pn = Lb - mt * 22;
;         u.A = HB + (size_t)mt * 256 * 1024; u.B = B + (size_t)pn * 256 * 1024; u.nt = 16; u.pm = mt; u.pn = pn; u.mode = 1; return true;
;     __device__ __forceinline__ void operator()(const f32x4 (&acc)[2][2][4][2], const Unit& u, int wr, int wc, int fr, int fq) const {
;     ...
;             const int f0 = 128 * u.pn + 32 * wc + 8 * fq + 4 * n;
;             f32x4 wa[3], wg[3];
; #pragma unroll
;             for (int j = 0; j < 3; ++j) { wa[j] = *(const f32x4*)(cw + j * 5632 + f0); wg[j] = *(const f32x4*)(cw + j * 5632 + 2816 + f0); }
;             const f32x4 ba = *(const f32x4*)(cb + f0), bg = *(const f32x4*)(cb + 2816 + f0);
.LBB0_106:
	v_mbcnt_lo_u32_b32 v236, -1, 0
	v_mbcnt_hi_u32_b32 v236, -1, v236
	v_lshrrev_b32_e32 v237, 3, v236
	v_lshlrev_b32_e32 v237, 3, v237
	v_add_u32_e32 v237, 0xa0, v237
	ds_bpermute_b32 v234, v237, v253
	v_add_u32_e32 v237, 4, v237
	ds_bpermute_b32 v235, v237, v253
	v_and_b32_e32 v224, 7, v236
	v_lshlrev_b32_e32 v224, 4, v224
	s_lshl_b32 s56, s18, 7
	s_add_i32 s56, s56, s94
	s_lshl_b32 s56, s56, 2
	v_add_u32_e32 v224, s56, v224
	v_mov_b32_e32 v225, 0
	s_waitcnt lgkmcnt(0)
	v_lshl_add_u64 v[234:235], v[224:225], 0, v[234:235]
	global_load_dwordx4 v[230:233], v[234:235], off
	s_add_i32 s10, s10, 1
	v_readlane_b32 s1, v254, 36
	s_mul_i32 s1, s10, s1
	v_readlane_b32 s16, v254, 34
	s_add_i32 s1, s1, s16
	v_readlane_b32 s3, v253, 37
	s_cmp_ge_i32 s1, s3
	v_readlane_b32 s17, v254, 35
	s_cbranch_scc0 .LBB0_111
	s_sub_i32 s3, s1, s3
	s_mov_b64 s[28:29], 0
	s_cmpk_lt_i32 s3, 0x6e
	s_mov_b64 s[16:17], 0
	s_cbranch_scc0 .LBB0_109
	s_mul_hi_i32 s11, s3, 0x2e8ba2e9
	s_lshr_b32 s16, s11, 31
	s_ashr_i32 s11, s11, 2
	s_add_i32 s26, s11, s16
	s_mul_i32 s11, s26, 0xffffffea
	s_add_i32 s24, s11, s3
	s_mov_b64 s[16:17], -1
	s_mov_b32 s11, 1
	s_mov_b64 s[30:31], 0x15500000
	s_and_b64 vcc, exec, s[28:29]
	s_cbranch_vccz .LBB0_112
	s_branch .LBB0_110

; __device__ __forceinline__ unsigned cvt_pk_bf16(float lo, float hi) { f32x2 v = {lo, hi}; bf16x2_t b = __builtin_convertvector(v, bf16x2_t); return __builtin_bit_cast(unsigned, b); }
; __device__ __forceinline__ float sigmoidf_(float v) { return __builtin_amdgcn_rcpf(1.0f + __builtin_amdgcn_exp2f(-1.4426950408889634f * v)); }
; __device__ __forceinline__ float dpp_shr1(float v) { return __builtin_bit_cast(float, __builtin_amdgcn_update_dpp(0, __builtin_bit_cast(int, v), 0x111, 0xf, 0xf, true)); }
;     __device__ __forceinline__ void operator()(const f32x4 (&acc)[2][2][4][2], const Unit& u, int wr, int wc, int fr, int fq) const {
;     ...
;         const size_t row0 = (size_t)256 * u.pm + 128 * wr + 8 * fr;
; #pragma unroll
;         for (int n = 0; n < 2; ++n) {
;             const int f0 = 128 * u.pn + 32 * wc + 8 * fq + 4 * n;
;             f32x4 wa[3], wg[3];
; #pragma unroll
;             for (int j = 0; j < 3; ++j) { wa[j] = *(const f32x4*)(cw + j * 5632 + f0); wg[j] = *(const f32x4*)(cw + j * 5632 + 2816 + f0); }
;             const f32x4 ba = *(const f32x4*)(cb + f0), bg = *(const f32x4*)(cb + 2816 + f0);
;             f32x4 pa, pg, na, ng;
; #pragma unroll
;             for (int e = 0; e < 4; ++e) { pa[e] = dpp_shr1(acc[1][0][3][n][e]); pg[e] = dpp_shr1(acc[1][1][3][n][e]); na[e] = dpp_shl1(acc[0][0][0][n][e]); ng[e] = dpp_shl1(acc[0][1][0][n][e]); }
; #pragma unroll
;             for (int k = 0; k < 8; ++k) {
;                 const f32x4 ua0 = (k == 0) ? pa : acc[(k - 1) >> 2][0][(k - 1) & 3][n], ua1 = acc[k >> 2][0][k & 3][n], ua2 = (k == 7) ? na : acc[(k + 1) >> 2][0][(k + 1) & 3][n];
;                 const f32x4 ug0 = (k == 0) ? pg : acc[(k - 1) >> 2][1][(k - 1) & 3][n], ug1 = acc[k >> 2][1][k & 3][n], ug2 = (k == 7) ? ng : acc[(k + 1) >> 2][1][(k + 1) & 3][n];
;                 const f32x4 ca = wa[0] * ua0 + wa[1] * ua1 + wa[2] * ua2 + ba, cg = wg[0] * ug0 + wg[1] * ug1 + wg[2] * ug2 + bg;
;                 u32x2 w; w.x = cvt_pk_bf16(cg[0] * sigmoidf_(cg[0]) * ca[0], cg[1] * sigmoidf_(cg[1]) * ca[1]); w.y = cvt_pk_bf16(cg[2] * sigmoidf_(cg[2]) * ca[2], cg[3] * sigmoidf_(cg[3]) * ca[3]);
;                 const bool edge = (k == 0 && fr == 0) || (k == 7 && fr == 15);
;                 if (!edge) *(u32x2*)(ACT + (row0 + k) * 2816 + f0) = w;
.LBB0_118:
	v_mov_b32_e32 v128, v212
	v_mov_b32_e32 v192, v197
	s_mov_b64 s[6:7], -1
	s_cmp_lg_u32 s2, 1
	v_lshl_add_u32 v215, v128, 3, s94
	s_cbranch_scc0 .LBB0_131
	s_add_i32 s57, s96, 0x20800
	v_lshl_add_u32 v247, v236, 4, s57
	v_lshl_add_u32 v248, v212, 5, s57
	s_ashr_i32 s1, s0, 31
	s_lshl_b64 s[2:3], s[0:1], 8
	s_add_u32 s2, s2, s35
	v_readlane_b32 s1, v254, 63
	s_addc_u32 s3, s3, s1
	s_lshl_b32 s1, s18, 7
	v_add_u32_e32 v172, s1, v215
	v_ashrrev_i32_e32 v173, 31, v172
	v_readlane_b32 s6, v253, 48
	v_lshlrev_b64 v[144:145], 2, v[172:173]
	v_readlane_b32 s7, v253, 49
	v_lshlrev_b32_e32 v174, 3, v192
	v_ashrrev_i32_e32 v175, 31, v174
	v_lshl_add_u64 v[128:129], s[6:7], 0, v[144:145]
	v_readlane_b32 s6, v253, 40
	v_readlane_b32 s7, v253, 41
	v_lshl_add_u64 v[174:175], s[2:3], 0, v[174:175]
	v_mov_b32_dpp v178, v76 row_shr:1 row_mask:0xf bank_mask:0xf bound_ctrl:1
	v_lshl_add_u64 v[132:133], s[6:7], 0, v[144:145]
	v_readlane_b32 s6, v253, 42
	v_readlane_b32 s7, v253, 43
	s_waitcnt vmcnt(14)
	ds_write_b128 v247, v[230:233]
	ds_read_b128 v[128:131], v248 offset:512
	s_nop 0
	ds_read_b128 v[136:139], v248
	v_lshl_add_u64 v[132:133], s[6:7], 0, v[144:145]
	v_readlane_b32 s6, v253, 44
	v_readlane_b32 s7, v253, 45
	v_mov_b32_dpp v182, v60 row_shr:1 row_mask:0xf bank_mask:0xf bound_ctrl:1
	v_mov_b32_dpp v188, v124 row_shl:1 row_mask:0xf bank_mask:0xf bound_ctrl:1
	v_lshl_add_u64 v[134:135], s[6:7], 0, v[144:145]
	v_readlane_b32 s6, v253, 46
	v_readlane_b32 s7, v253, 47
	ds_read_b128 v[140:143], v248 offset:128
	ds_read_b128 v[152:155], v248 offset:256
	v_lshl_add_u64 v[132:133], s[6:7], 0, v[144:145]
	v_readlane_b32 s6, v253, 50
	v_readlane_b32 s7, v253, 51
	v_mov_b32_dpp v198, v120 row_shl:1 row_mask:0xf bank_mask:0xf bound_ctrl:1
	v_mov_b32_dpp v179, v77 row_shr:1 row_mask:0xf bank_mask:0xf bound_ctrl:1
	v_lshl_add_u64 v[146:147], s[6:7], 0, v[144:145]
	v_readlane_b32 s6, v253, 52
	v_readlane_b32 s7, v253, 53
	ds_read_b128 v[132:135], v248 offset:384
	s_nop 0
	ds_read_b128 v[148:151], v248 offset:640
	v_lshl_add_u64 v[146:147], s[6:7], 0, v[144:145]
	v_readlane_b32 s6, v253, 54
	v_readlane_b32 s7, v253, 55
	v_mov_b32_dpp v183, v61 row_shr:1 row_mask:0xf bank_mask:0xf bound_ctrl:1
	v_mov_b32_dpp v189, v125 row_shl:1 row_mask:0xf bank_mask:0xf bound_ctrl:1
	v_lshl_add_u64 v[156:157], s[6:7], 0, v[144:145]
	ds_read_b128 v[144:147], v248 offset:768
	s_nop 0
	ds_read_b128 v[156:159], v248 offset:896
	v_mov_b32_dpp v199, v121 row_shl:1 row_mask:0xf bank_mask:0xf bound_ctrl:1
	v_mov_b32_dpp v180, v78 row_shr:1 row_mask:0xf bank_mask:0xf bound_ctrl:1
	v_mov_b32_dpp v184, v62 row_shr:1 row_mask:0xf bank_mask:0xf bound_ctrl:1
	v_mov_b32_dpp v186, v126 row_shl:1 row_mask:0xf bank_mask:0xf bound_ctrl:1
	v_mov_b32_dpp v190, v122 row_shl:1 row_mask:0xf bank_mask:0xf bound_ctrl:1
	v_mov_b32_dpp v181, v79 row_shr:1 row_mask:0xf bank_mask:0xf bound_ctrl:1
	v_mov_b32_dpp v185, v63 row_shr:1 row_mask:0xf bank_mask:0xf bound_ctrl:1
	v_mov_b32_dpp v187, v127 row_shl:1 row_mask:0xf bank_mask:0xf bound_ctrl:1
	v_mov_b32_dpp v191, v123 row_shl:1 row_mask:0xf bank_mask:0xf bound_ctrl:1
	v_cmp_ne_u32_e64 s[8:9], 0, v192
	s_and_saveexec_b64 s[2:3], s[8:9]
	s_xor_b64 s[6:7], exec, s[2:3]
	s_cbranch_execz .LBB0_121
	s_waitcnt lgkmcnt(0)
	v_pk_mul_f32 v[182:183], v[136:137], v[182:183]
	v_pk_mul_f32 v[176:177], v[138:139], v[184:185]
	v_pk_fma_f32 v[182:183], v[120:121], v[152:153], v[182:183]
	v_pk_mul_f32 v[178:179], v[128:129], v[178:179]
	v_pk_fma_f32 v[182:183], v[104:105], v[148:149], v[182:183]
	v_pk_fma_f32 v[178:179], v[124:125], v[140:141], v[178:179]
	v_pk_add_f32 v[182:183], v[156:157], v[182:183]
	v_pk_fma_f32 v[176:177], v[122:123], v[154:155], v[176:177]
	v_mul_f32_e32 v184, 0xbfb8aa3b, v182
	v_mul_f32_e32 v185, 0xbfb8aa3b, v183
	v_exp_f32_e32 v184, v184
	v_exp_f32_e32 v185, v185
	v_pk_fma_f32 v[178:179], v[116:117], v[132:133], v[178:179]
	v_pk_fma_f32 v[176:177], v[106:107], v[150:151], v[176:177]
	v_add_f32_e32 v184, 1.0, v184
	v_add_f32_e32 v185, 1.0, v185
	v_rcp_f32_e32 v184, v184
	v_rcp_f32_e32 v185, v185
	v_pk_add_f32 v[178:179], v[144:145], v[178:179]
	v_pk_add_f32 v[176:177], v[158:159], v[176:177]
	v_pk_mul_f32 v[180:181], v[130:131], v[180:181]
	v_pk_mul_f32 v[182:183], v[182:183], v[184:185]
	v_pk_fma_f32 v[180:181], v[126:127], v[142:143], v[180:181]
	v_pk_mul_f32 v[178:179], v[178:179], v[182:183]
	v_pk_fma_f32 v[180:181], v[118:119], v[134:135], v[180:181]
	v_cvt_pk_bf16_f32 v178, v178, v179
	v_mul_f32_e32 v179, 0xbfb8aa3b, v176
	v_exp_f32_e32 v179, v179
	v_pk_add_f32 v[180:181], v[146:147], v[180:181]
	s_movk_i32 s19, 0x1600
	v_add_f32_e32 v179, 1.0, v179
	v_rcp_f32_e32 v182, v179
	v_mul_f32_e32 v179, 0xbfb8aa3b, v177
	v_exp_f32_e32 v179, v179
	s_nop 0
	v_add_f32_e32 v179, 1.0, v179
	v_rcp_f32_e32 v183, v179
	s_nop 0
	v_pk_mul_f32 v[176:177], v[176:177], v[182:183]
	s_nop 0
	v_pk_mul_f32 v[176:177], v[180:181], v[176:177]
	s_nop 0
	v_cvt_pk_bf16_f32 v179, v176, v177
	v_mad_u64_u32 v[176:177], s[2:3], v174, s19, 0
	v_readlane_b32 s2, v254, 38
	v_readlane_b32 s3, v254, 39
	v_mad_i32_i24 v177, v175, s19, v177
	s_nop 0
	v_mov_b64_e32 v[180:181], s[2:3]
	v_mad_u64_u32 v[180:181], s[2:3], v174, s19, v[180:181]
	v_mad_i32_i24 v181, v175, s19, v181
	v_lshl_add_u64 v[174:175], v[172:173], 1, v[180:181]
	flat_store_dwordx2 v[174:175], v[178:179]

; __device__ __forceinline__ unsigned cvt_pk_bf16(float lo, float hi) { f32x2 v = {lo, hi}; bf16x2_t b = __builtin_convertvector(v, bf16x2_t); return __builtin_bit_cast(unsigned, b); }
; __device__ __forceinline__ float sigmoidf_(float v) { return __builtin_amdgcn_rcpf(1.0f + __builtin_amdgcn_exp2f(-1.4426950408889634f * v)); }
; __device__ __forceinline__ float dpp_shr1(float v) { return __builtin_bit_cast(float, __builtin_amdgcn_update_dpp(0, __builtin_bit_cast(int, v), 0x111, 0xf, 0xf, true)); }
; __device__ __forceinline__ float dpp_shl1(float v) { return __builtin_bit_cast(float, __builtin_amdgcn_update_dpp(0, __builtin_bit_cast(int, v), 0x101, 0xf, 0xf, true)); }
;     __device__ __forceinline__ void operator()(const f32x4 (&acc)[2][2][4][2], const Unit& u, int wr, int wc, int fr, int fq) const {
;     ...
;         for (int n = 0; n < 2; ++n) {
;             const int f0 = 128 * u.pn + 32 * wc + 8 * fq + 4 * n;
;             f32x4 wa[3], wg[3];
; #pragma unroll
;             for (int j = 0; j < 3; ++j) { wa[j] = *(const f32x4*)(cw + j * 5632 + f0); wg[j] = *(const f32x4*)(cw + j * 5632 + 2816 + f0); }
;             const f32x4 ba = *(const f32x4*)(cb + f0), bg = *(const f32x4*)(cb + 2816 + f0);
;             f32x4 pa, pg, na, ng;
; #pragma unroll
;             for (int e = 0; e < 4; ++e) { pa[e] = dpp_shr1(acc[1][0][3][n][e]); pg[e] = dpp_shr1(acc[1][1][3][n][e]); na[e] = dpp_shl1(acc[0][0][0][n][e]); ng[e] = dpp_shl1(acc[0][1][0][n][e]); }
; #pragma unroll
;             for (int k = 0; k < 8; ++k) {
;                 const f32x4 ua0 = (k == 0) ? pa : acc[(k - 1) >> 2][0][(k - 1) & 3][n], ua1 = acc[k >> 2][0][k & 3][n], ua2 = (k == 7) ? na : acc[(k + 1) >> 2][0][(k + 1) & 3][n];
;                 const f32x4 ug0 = (k == 0) ? pg : acc[(k - 1) >> 2][1][(k - 1) & 3][n], ug1 = acc[k >> 2][1][k & 3][n], ug2 = (k == 7) ? ng : acc[(k + 1) >> 2][1][(k + 1) & 3][n];
;                 const f32x4 ca = wa[0] * ua0 + wa[1] * ua1 + wa[2] * ua2 + ba, cg = wg[0] * ug0 + wg[1] * ug1 + wg[2] * ug2 + bg;
;                 u32x2 w; w.x = cvt_pk_bf16(cg[0] * sigmoidf_(cg[0]) * ca[0], cg[1] * sigmoidf_(cg[1]) * ca[1]); w.y = cvt_pk_bf16(cg[2] * sigmoidf_(cg[2]) * ca[2], cg[3] * sigmoidf_(cg[3]) * ca[3]);
;                 const bool edge = (k == 0 && fr == 0) || (k == 7 && fr == 15);
;                 if (!edge) *(u32x2*)(ACT + (row0 + k) * 2816 + f0) = w;
.LBB0_125:
	s_or_b64 exec, exec, s[28:29]
	v_add3_u32 v202, v215, s1, 4
	v_ashrrev_i32_e32 v203, 31, v202
	v_readlane_b32 s2, v253, 48
	v_lshlrev_b64 v[144:145], 2, v[202:203]
	v_readlane_b32 s3, v253, 49
	v_mov_b32_dpp v204, v12 row_shr:1 row_mask:0xf bank_mask:0xf bound_ctrl:1
	v_mov_b32_dpp v208, v0 row_shr:1 row_mask:0xf bank_mask:0xf bound_ctrl:1
	v_lshl_add_u64 v[128:129], s[2:3], 0, v[144:145]
	v_readlane_b32 s2, v253, 40
	v_readlane_b32 s3, v253, 41
	v_mov_b32_dpp v188, v64 row_shl:1 row_mask:0xf bank_mask:0xf bound_ctrl:1
	v_mov_b32_dpp v198, v56 row_shl:1 row_mask:0xf bank_mask:0xf bound_ctrl:1
	v_lshl_add_u64 v[132:133], s[2:3], 0, v[144:145]
	v_readlane_b32 s2, v253, 42
	v_readlane_b32 s3, v253, 43
	ds_read_b128 v[128:131], v248 offset:528
	s_nop 0
	ds_read_b128 v[136:139], v248 offset:16
	v_lshl_add_u64 v[132:133], s[2:3], 0, v[144:145]
	v_readlane_b32 s2, v253, 44
	v_readlane_b32 s3, v253, 45
	v_mov_b32_dpp v205, v13 row_shr:1 row_mask:0xf bank_mask:0xf bound_ctrl:1
	v_mov_b32_dpp v209, v1 row_shr:1 row_mask:0xf bank_mask:0xf bound_ctrl:1
	v_lshl_add_u64 v[134:135], s[2:3], 0, v[144:145]
	v_readlane_b32 s2, v253, 46
	v_readlane_b32 s3, v253, 47
	ds_read_b128 v[140:143], v248 offset:144
	ds_read_b128 v[152:155], v248 offset:272
	v_lshl_add_u64 v[132:133], s[2:3], 0, v[144:145]
	v_readlane_b32 s2, v253, 50
	v_readlane_b32 s3, v253, 51
	v_mov_b32_dpp v189, v65 row_shl:1 row_mask:0xf bank_mask:0xf bound_ctrl:1
	v_mov_b32_dpp v199, v57 row_shl:1 row_mask:0xf bank_mask:0xf bound_ctrl:1
	v_lshl_add_u64 v[146:147], s[2:3], 0, v[144:145]
	v_readlane_b32 s2, v253, 52
	v_readlane_b32 s3, v253, 53
	ds_read_b128 v[132:135], v248 offset:400
	s_nop 0
	ds_read_b128 v[148:151], v248 offset:656
	v_lshl_add_u64 v[146:147], s[2:3], 0, v[144:145]
	v_readlane_b32 s2, v253, 54
	v_readlane_b32 s3, v253, 55
	v_mov_b32_dpp v206, v14 row_shr:1 row_mask:0xf bank_mask:0xf bound_ctrl:1
	v_mov_b32_dpp v210, v2 row_shr:1 row_mask:0xf bank_mask:0xf bound_ctrl:1
	v_lshl_add_u64 v[156:157], s[2:3], 0, v[144:145]
	ds_read_b128 v[144:147], v248 offset:784
	s_nop 0
	ds_read_b128 v[156:159], v248 offset:912
	v_mov_b32_dpp v186, v66 row_shl:1 row_mask:0xf bank_mask:0xf bound_ctrl:1
	v_mov_b32_dpp v190, v58 row_shl:1 row_mask:0xf bank_mask:0xf bound_ctrl:1
	v_mov_b32_dpp v207, v15 row_shr:1 row_mask:0xf bank_mask:0xf bound_ctrl:1
	v_mov_b32_dpp v211, v3 row_shr:1 row_mask:0xf bank_mask:0xf bound_ctrl:1
	v_mov_b32_dpp v187, v67 row_shl:1 row_mask:0xf bank_mask:0xf bound_ctrl:1
	v_mov_b32_dpp v191, v59 row_shl:1 row_mask:0xf bank_mask:0xf bound_ctrl:1
	v_lshl_add_u64 v[172:173], v[202:203], 1, v[200:201]
	s_and_saveexec_b64 s[28:29], s[8:9]
	s_cbranch_execz .LBB0_127
	s_waitcnt lgkmcnt(0)
	v_pk_mul_f32 v[208:209], v[136:137], v[208:209]
	v_pk_mul_f32 v[200:201], v[138:139], v[210:211]
	v_pk_fma_f32 v[208:209], v[56:57], v[152:153], v[208:209]
	v_pk_mul_f32 v[204:205], v[128:129], v[204:205]
	v_pk_fma_f32 v[208:209], v[40:41], v[148:149], v[208:209]
	v_pk_fma_f32 v[204:205], v[64:65], v[140:141], v[204:205]
	v_pk_add_f32 v[208:209], v[156:157], v[208:209]
	v_pk_fma_f32 v[200:201], v[58:59], v[154:155], v[200:201]
	v_mul_f32_e32 v210, 0xbfb8aa3b, v208
	v_mul_f32_e32 v211, 0xbfb8aa3b, v209
	v_exp_f32_e32 v210, v210
	v_exp_f32_e32 v211, v211
	v_pk_fma_f32 v[204:205], v[52:53], v[132:133], v[204:205]
	v_pk_fma_f32 v[200:201], v[42:43], v[150:151], v[200:201]
	v_add_f32_e32 v210, 1.0, v210
	v_add_f32_e32 v211, 1.0, v211
	v_rcp_f32_e32 v210, v210
	v_rcp_f32_e32 v211, v211
	v_pk_add_f32 v[204:205], v[144:145], v[204:205]
	v_pk_add_f32 v[200:201], v[158:159], v[200:201]
	v_pk_mul_f32 v[206:207], v[130:131], v[206:207]
	v_pk_mul_f32 v[208:209], v[208:209], v[210:211]
	v_pk_fma_f32 v[206:207], v[66:67], v[142:143], v[206:207]
	v_pk_mul_f32 v[204:205], v[204:205], v[208:209]
	v_pk_fma_f32 v[206:207], v[54:55], v[134:135], v[206:207]
	v_cvt_pk_bf16_f32 v204, v204, v205
	v_mul_f32_e32 v205, 0xbfb8aa3b, v200
	v_exp_f32_e32 v205, v205
	v_pk_add_f32 v[206:207], v[146:147], v[206:207]
	v_add_f32_e32 v205, 1.0, v205
	v_rcp_f32_e32 v208, v205
	v_mul_f32_e32 v205, 0xbfb8aa3b, v201
	v_exp_f32_e32 v205, v205
	s_nop 0
	v_add_f32_e32 v205, 1.0, v205
	v_rcp_f32_e32 v209, v205
	s_nop 0
	v_pk_mul_f32 v[200:201], v[200:201], v[208:209]
	s_nop 0
	v_pk_mul_f32 v[200:201], v[206:207], v[200:201]
	s_nop 0
	v_cvt_pk_bf16_f32 v205, v200, v201
	flat_store_dwordx2 v[172:173], v[204:205]
